# k9 rel-bias section per step: one base add, ds_read2_b32 with swapped offsets into final registers, in-place v_pk_add (32 v_mov + 15 v_add removed per step)
# speedup vs baseline: 1.0070x; 1.0050x over previous
.LBB9_40:
	s_add_i32 s67, s63, s66
	s_cmp_le_i32 s67, s45
	s_cselect_b64 s[38:39], -1, 0
	s_and_b64 s[38:39], s[4:5], s[38:39]
	s_cmp_ge_i32 s67, s46
	s_cselect_b64 s[40:41], -1, 0
	s_and_b64 s[38:39], s[38:39], s[40:41]
	s_andn2_b64 vcc, exec, s[38:39]
	s_cbranch_vccnz .LBB9_49
	v_add_u32_e32 v36, v35, v128
	v_add_u32_e32 v66, s47, v144
	ds_read_b128 v[120:123], v36
	ds_read_b128 v[124:127], v36 offset:32
	ds_read_b128 v[146:149], v36 offset:8704
	ds_read_b128 v[150:153], v36 offset:8736
	ds_read_b128 v[154:157], v36 offset:64
	ds_read_b128 v[158:161], v36 offset:96
	ds_read_b128 v[162:165], v36 offset:8768
	ds_read_b128 v[166:169], v36 offset:8800
	v_add_u32_e32 v70, 0x12c10, v66
	ds_read2_b32 v[36:37], v70 offset0:59 offset1:58
	ds_read2_b32 v[38:39], v70 offset0:57 offset1:56
	ds_read2_b32 v[40:41], v70 offset0:51 offset1:50
	ds_read2_b32 v[42:43], v70 offset0:49 offset1:48
	ds_read2_b32 v[44:45], v70 offset0:43 offset1:42
	ds_read2_b32 v[46:47], v70 offset0:41 offset1:40
	ds_read2_b32 v[48:49], v70 offset0:35 offset1:34
	ds_read2_b32 v[50:51], v70 offset0:33 offset1:32
	ds_read2_b32 v[52:53], v70 offset0:27 offset1:26
	ds_read2_b32 v[54:55], v70 offset0:25 offset1:24
	ds_read2_b32 v[56:57], v70 offset0:19 offset1:18
	ds_read2_b32 v[58:59], v70 offset0:17 offset1:16
	ds_read2_b32 v[60:61], v70 offset0:11 offset1:10
	ds_read2_b32 v[62:63], v70 offset0:9 offset1:8
	ds_read2_b32 v[64:65], v70 offset0:3 offset1:2
	ds_read2_b32 v[66:67], v70 offset0:1 offset1:0
	s_waitcnt lgkmcnt(15)
	v_pk_add_f32 v[36:37], v[36:37], v[138:139] op_sel_hi:[1,0] neg_lo:[0,1] neg_hi:[0,1]
	s_waitcnt lgkmcnt(14)
	v_pk_add_f32 v[38:39], v[38:39], v[138:139] op_sel_hi:[1,0] neg_lo:[0,1] neg_hi:[0,1]
	s_waitcnt lgkmcnt(13)
	v_pk_add_f32 v[40:41], v[40:41], v[138:139] op_sel_hi:[1,0] neg_lo:[0,1] neg_hi:[0,1]
	s_waitcnt lgkmcnt(12)
	v_pk_add_f32 v[42:43], v[42:43], v[138:139] op_sel_hi:[1,0] neg_lo:[0,1] neg_hi:[0,1]
	s_waitcnt lgkmcnt(11)
	v_pk_add_f32 v[44:45], v[44:45], v[138:139] op_sel_hi:[1,0] neg_lo:[0,1] neg_hi:[0,1]
	s_waitcnt lgkmcnt(10)
	v_pk_add_f32 v[46:47], v[46:47], v[138:139] op_sel_hi:[1,0] neg_lo:[0,1] neg_hi:[0,1]
	s_waitcnt lgkmcnt(9)
	v_pk_add_f32 v[48:49], v[48:49], v[138:139] op_sel_hi:[1,0] neg_lo:[0,1] neg_hi:[0,1]
	s_waitcnt lgkmcnt(8)
	v_pk_add_f32 v[50:51], v[50:51], v[138:139] op_sel_hi:[1,0] neg_lo:[0,1] neg_hi:[0,1]
	s_waitcnt lgkmcnt(7)
	v_pk_add_f32 v[52:53], v[52:53], v[138:139] op_sel_hi:[1,0] neg_lo:[0,1] neg_hi:[0,1]
	s_waitcnt lgkmcnt(6)
	v_pk_add_f32 v[54:55], v[54:55], v[138:139] op_sel_hi:[1,0] neg_lo:[0,1] neg_hi:[0,1]
	s_waitcnt lgkmcnt(5)
	v_pk_add_f32 v[56:57], v[56:57], v[138:139] op_sel_hi:[1,0] neg_lo:[0,1] neg_hi:[0,1]
	s_waitcnt lgkmcnt(4)
	v_pk_add_f32 v[58:59], v[58:59], v[138:139] op_sel_hi:[1,0] neg_lo:[0,1] neg_hi:[0,1]
	s_waitcnt lgkmcnt(3)
	v_pk_add_f32 v[60:61], v[60:61], v[138:139] op_sel_hi:[1,0] neg_lo:[0,1] neg_hi:[0,1]
	s_waitcnt lgkmcnt(2)
	v_pk_add_f32 v[62:63], v[62:63], v[138:139] op_sel_hi:[1,0] neg_lo:[0,1] neg_hi:[0,1]
	s_waitcnt lgkmcnt(1)
	v_pk_add_f32 v[64:65], v[64:65], v[138:139] op_sel_hi:[1,0] neg_lo:[0,1] neg_hi:[0,1]
	s_waitcnt lgkmcnt(0)
	v_pk_add_f32 v[66:67], v[66:67], v[138:139] op_sel_hi:[1,0] neg_lo:[0,1] neg_hi:[0,1]
	s_xor_b64 s[38:39], s[12:13], -1
	v_mfma_f32_32x32x16_bf16 v[36:51], v[120:123], v[72:75], v[36:51]
	v_mfma_f32_32x32x16_bf16 v[52:67], v[146:149], v[72:75], v[52:67]
	v_mfma_f32_32x32x16_bf16 v[36:51], v[124:127], v[76:79], v[36:51]
	ds_read_b64_tr_b16 v[124:125], v129 offset:34816
	ds_read_b64_tr_b16 v[126:127], v129 offset:37376
	ds_read_b64_tr_b16 v[122:123], v129 offset:37440
	ds_read_b64_tr_b16 v[120:121], v129 offset:34880
	v_mfma_f32_32x32x16_bf16 v[52:67], v[150:153], v[76:79], v[52:67]
	v_mfma_f32_32x32x16_bf16 v[36:51], v[154:157], v[80:83], v[36:51]
	v_mfma_f32_32x32x16_bf16 v[52:67], v[162:165], v[80:83], v[52:67]
	v_mfma_f32_32x32x16_bf16 v[36:51], v[158:161], v[84:87], v[36:51]
	v_mfma_f32_32x32x16_bf16 v[52:67], v[166:169], v[84:87], v[52:67]
	s_nop 11
	v_max_f32_e32 v68, v52, v52
	v_max_f32_e32 v70, v36, v36
	v_max_f32_e32 v68, v70, v68
	v_max3_f32 v68, v68, v37, v38
	v_max3_f32 v68, v68, v39, v40
	v_max3_f32 v68, v68, v41, v42
	v_max3_f32 v68, v68, v43, v44
	v_max3_f32 v68, v68, v45, v46
	v_max3_f32 v68, v68, v47, v48
	v_max3_f32 v68, v68, v49, v50
	v_max3_f32 v68, v68, v51, v53
	v_max3_f32 v68, v68, v54, v55
	v_max3_f32 v68, v68, v56, v57
	v_max3_f32 v68, v68, v58, v59
	v_max3_f32 v68, v68, v60, v61
	v_max3_f32 v68, v68, v62, v63
	v_max3_f32 v68, v68, v64, v65
	v_max3_f32 v68, v68, v66, v67
	v_mov_b32_e32 v70, v68
	s_nop 1
	v_permlane32_swap_b32_e32 v68, v70
	v_max_f32_e32 v70, v70, v70
	v_max_f32_e32 v68, v68, v68
	v_max_f32_e32 v70, v68, v70
	s_and_b64 vcc, exec, s[38:39]
	s_cbranch_vccz .LBB9_75
	v_cmp_lt_f32_e32 vcc, s57, v70
	s_mov_b64 s[40:41], 0
	s_mov_b64 s[38:39], 0
	s_cbranch_vccz .LBB9_44
	v_max_f32_e32 v68, v70, v70
	v_max_f32_e32 v68, 0, v68
	s_mov_b64 s[38:39], -1

.LBB9_59:
	s_add_i32 s67, s67, 1
	s_cmp_le_i32 s67, s45
	s_cselect_b64 s[40:41], -1, 0
	s_and_b64 s[40:41], s[4:5], s[40:41]
	s_cmp_ge_i32 s67, s46
	s_cselect_b64 s[66:67], -1, 0
	s_and_b64 s[40:41], s[40:41], s[66:67]
	s_andn2_b64 vcc, exec, s[40:41]
	s_cbranch_vccnz .LBB9_68
	v_add_u32_e32 v36, v35, v128
	v_add_u32_e32 v66, s62, v143
	ds_read_b128 v[120:123], v36 offset:17408
	ds_read_b128 v[124:127], v36 offset:17440
	ds_read_b128 v[146:149], v36 offset:26112
	ds_read_b128 v[150:153], v36 offset:26144
	ds_read_b128 v[154:157], v36 offset:17472
	ds_read_b128 v[158:161], v36 offset:17504
	ds_read_b128 v[162:165], v36 offset:26176
	ds_read_b128 v[166:169], v36 offset:26208
	v_add_u32_e32 v70, 0x12b10, v66
	ds_read2_b32 v[36:37], v70 offset0:59 offset1:58
	ds_read2_b32 v[38:39], v70 offset0:57 offset1:56
	ds_read2_b32 v[40:41], v70 offset0:51 offset1:50
	ds_read2_b32 v[42:43], v70 offset0:49 offset1:48
	ds_read2_b32 v[44:45], v70 offset0:43 offset1:42
	ds_read2_b32 v[46:47], v70 offset0:41 offset1:40
	ds_read2_b32 v[48:49], v70 offset0:35 offset1:34
	ds_read2_b32 v[50:51], v70 offset0:33 offset1:32
	ds_read2_b32 v[52:53], v70 offset0:27 offset1:26
	ds_read2_b32 v[54:55], v70 offset0:25 offset1:24
	ds_read2_b32 v[56:57], v70 offset0:19 offset1:18
	ds_read2_b32 v[58:59], v70 offset0:17 offset1:16
	ds_read2_b32 v[60:61], v70 offset0:11 offset1:10
	ds_read2_b32 v[62:63], v70 offset0:9 offset1:8
	ds_read2_b32 v[64:65], v70 offset0:3 offset1:2
	ds_read2_b32 v[66:67], v70 offset0:1 offset1:0
	s_waitcnt lgkmcnt(15)
	v_pk_add_f32 v[36:37], v[36:37], v[138:139] op_sel_hi:[1,0] neg_lo:[0,1] neg_hi:[0,1]
	s_waitcnt lgkmcnt(14)
	v_pk_add_f32 v[38:39], v[38:39], v[138:139] op_sel_hi:[1,0] neg_lo:[0,1] neg_hi:[0,1]
	s_waitcnt lgkmcnt(13)
	v_pk_add_f32 v[40:41], v[40:41], v[138:139] op_sel_hi:[1,0] neg_lo:[0,1] neg_hi:[0,1]
	s_waitcnt lgkmcnt(12)
	v_pk_add_f32 v[42:43], v[42:43], v[138:139] op_sel_hi:[1,0] neg_lo:[0,1] neg_hi:[0,1]
	s_waitcnt lgkmcnt(11)
	v_pk_add_f32 v[44:45], v[44:45], v[138:139] op_sel_hi:[1,0] neg_lo:[0,1] neg_hi:[0,1]
	s_waitcnt lgkmcnt(10)
	v_pk_add_f32 v[46:47], v[46:47], v[138:139] op_sel_hi:[1,0] neg_lo:[0,1] neg_hi:[0,1]
	s_waitcnt lgkmcnt(9)
	v_pk_add_f32 v[48:49], v[48:49], v[138:139] op_sel_hi:[1,0] neg_lo:[0,1] neg_hi:[0,1]
	s_waitcnt lgkmcnt(8)
	v_pk_add_f32 v[50:51], v[50:51], v[138:139] op_sel_hi:[1,0] neg_lo:[0,1] neg_hi:[0,1]
	s_waitcnt lgkmcnt(7)
	v_pk_add_f32 v[52:53], v[52:53], v[138:139] op_sel_hi:[1,0] neg_lo:[0,1] neg_hi:[0,1]
	s_waitcnt lgkmcnt(6)
	v_pk_add_f32 v[54:55], v[54:55], v[138:139] op_sel_hi:[1,0] neg_lo:[0,1] neg_hi:[0,1]
	s_waitcnt lgkmcnt(5)
	v_pk_add_f32 v[56:57], v[56:57], v[138:139] op_sel_hi:[1,0] neg_lo:[0,1] neg_hi:[0,1]
	s_waitcnt lgkmcnt(4)
	v_pk_add_f32 v[58:59], v[58:59], v[138:139] op_sel_hi:[1,0] neg_lo:[0,1] neg_hi:[0,1]
	s_waitcnt lgkmcnt(3)
	v_pk_add_f32 v[60:61], v[60:61], v[138:139] op_sel_hi:[1,0] neg_lo:[0,1] neg_hi:[0,1]
	s_waitcnt lgkmcnt(2)
	v_pk_add_f32 v[62:63], v[62:63], v[138:139] op_sel_hi:[1,0] neg_lo:[0,1] neg_hi:[0,1]
	s_waitcnt lgkmcnt(1)
	v_pk_add_f32 v[64:65], v[64:65], v[138:139] op_sel_hi:[1,0] neg_lo:[0,1] neg_hi:[0,1]
	s_waitcnt lgkmcnt(0)
	v_pk_add_f32 v[66:67], v[66:67], v[138:139] op_sel_hi:[1,0] neg_lo:[0,1] neg_hi:[0,1]
	v_mfma_f32_32x32x16_bf16 v[36:51], v[120:123], v[72:75], v[36:51]
	s_nop 0
	v_mfma_f32_32x32x16_bf16 v[52:67], v[146:149], v[72:75], v[52:67]
	v_mfma_f32_32x32x16_bf16 v[36:51], v[124:127], v[76:79], v[36:51]
	ds_read_b64_tr_b16 v[124:125], v129 offset:55296
	ds_read_b64_tr_b16 v[126:127], v129 offset:57856
	ds_read_b64_tr_b16 v[122:123], v129 offset:57920
	ds_read_b64_tr_b16 v[120:121], v129 offset:55360
	v_mfma_f32_32x32x16_bf16 v[52:67], v[150:153], v[76:79], v[52:67]
	v_mfma_f32_32x32x16_bf16 v[36:51], v[154:157], v[80:83], v[36:51]
	v_mfma_f32_32x32x16_bf16 v[52:67], v[162:165], v[80:83], v[52:67]
	v_mfma_f32_32x32x16_bf16 v[36:51], v[158:161], v[84:87], v[36:51]
	v_mfma_f32_32x32x16_bf16 v[52:67], v[166:169], v[84:87], v[52:67]
	s_nop 11
	v_max_f32_e32 v68, v52, v52
	v_max_f32_e32 v70, v36, v36
	v_max_f32_e32 v68, v70, v68
	v_max3_f32 v68, v68, v37, v38
	v_max3_f32 v68, v68, v39, v40
	v_max3_f32 v68, v68, v41, v42
	v_max3_f32 v68, v68, v43, v44
	v_max3_f32 v68, v68, v45, v46
	v_max3_f32 v68, v68, v47, v48
	v_max3_f32 v68, v68, v49, v50
	v_max3_f32 v68, v68, v51, v53
	v_max3_f32 v68, v68, v54, v55
	v_max3_f32 v68, v68, v56, v57
	v_max3_f32 v68, v68, v58, v59
	v_max3_f32 v68, v68, v60, v61
	v_max3_f32 v68, v68, v62, v63
	v_max3_f32 v68, v68, v64, v65
	v_max3_f32 v68, v68, v66, v67
	v_mov_b32_e32 v70, v68
	s_nop 1
	v_permlane32_swap_b32_e32 v68, v70
	v_max_f32_e32 v70, v70, v70
	v_max_f32_e32 v68, v68, v68
	v_max_f32_e32 v70, v68, v70
	s_and_b64 vcc, exec, s[38:39]
	s_cbranch_vccz .LBB9_76
	v_cmp_lt_f32_e32 vcc, s57, v70
	s_mov_b64 s[40:41], 0
	s_mov_b64 s[38:39], 0
	s_cbranch_vccz .LBB9_63
	v_max_f32_e32 v68, v70, v70
	v_max_f32_e32 v68, 0, v68
	s_mov_b64 s[38:39], -1

.LBB9_129:
	s_add_i32 s70, s66, s69
	s_cmp_le_i32 s70, s43
	s_cselect_b64 s[36:37], -1, 0
	s_and_b64 s[36:37], s[2:3], s[36:37]
	s_cmp_ge_i32 s70, s44
	s_cselect_b64 s[38:39], -1, 0
	s_and_b64 s[36:37], s[36:37], s[38:39]
	s_andn2_b64 vcc, exec, s[36:37]
	s_cbranch_vccnz .LBB9_138
	v_add_u32_e32 v36, v35, v128
	v_add_u32_e32 v66, s45, v144
	ds_read_b128 v[120:123], v36
	ds_read_b128 v[124:127], v36 offset:32
	ds_read_b128 v[146:149], v36 offset:8704
	ds_read_b128 v[150:153], v36 offset:8736
	ds_read_b128 v[154:157], v36 offset:64
	ds_read_b128 v[158:161], v36 offset:96
	ds_read_b128 v[162:165], v36 offset:8768
	ds_read_b128 v[166:169], v36 offset:8800
	v_add_u32_e32 v70, 0x12c10, v66
	ds_read2_b32 v[36:37], v70 offset0:59 offset1:58
	ds_read2_b32 v[38:39], v70 offset0:57 offset1:56
	ds_read2_b32 v[40:41], v70 offset0:51 offset1:50
	ds_read2_b32 v[42:43], v70 offset0:49 offset1:48
	ds_read2_b32 v[44:45], v70 offset0:43 offset1:42
	ds_read2_b32 v[46:47], v70 offset0:41 offset1:40
	ds_read2_b32 v[48:49], v70 offset0:35 offset1:34
	ds_read2_b32 v[50:51], v70 offset0:33 offset1:32
	ds_read2_b32 v[52:53], v70 offset0:27 offset1:26
	ds_read2_b32 v[54:55], v70 offset0:25 offset1:24
	ds_read2_b32 v[56:57], v70 offset0:19 offset1:18
	ds_read2_b32 v[58:59], v70 offset0:17 offset1:16
	ds_read2_b32 v[60:61], v70 offset0:11 offset1:10
	ds_read2_b32 v[62:63], v70 offset0:9 offset1:8
	ds_read2_b32 v[64:65], v70 offset0:3 offset1:2
	ds_read2_b32 v[66:67], v70 offset0:1 offset1:0
	s_waitcnt lgkmcnt(15)
	v_pk_add_f32 v[36:37], v[36:37], v[138:139] op_sel_hi:[1,0] neg_lo:[0,1] neg_hi:[0,1]
	s_waitcnt lgkmcnt(14)
	v_pk_add_f32 v[38:39], v[38:39], v[138:139] op_sel_hi:[1,0] neg_lo:[0,1] neg_hi:[0,1]
	s_waitcnt lgkmcnt(13)
	v_pk_add_f32 v[40:41], v[40:41], v[138:139] op_sel_hi:[1,0] neg_lo:[0,1] neg_hi:[0,1]
	s_waitcnt lgkmcnt(12)
	v_pk_add_f32 v[42:43], v[42:43], v[138:139] op_sel_hi:[1,0] neg_lo:[0,1] neg_hi:[0,1]
	s_waitcnt lgkmcnt(11)
	v_pk_add_f32 v[44:45], v[44:45], v[138:139] op_sel_hi:[1,0] neg_lo:[0,1] neg_hi:[0,1]
	s_waitcnt lgkmcnt(10)
	v_pk_add_f32 v[46:47], v[46:47], v[138:139] op_sel_hi:[1,0] neg_lo:[0,1] neg_hi:[0,1]
	s_waitcnt lgkmcnt(9)
	v_pk_add_f32 v[48:49], v[48:49], v[138:139] op_sel_hi:[1,0] neg_lo:[0,1] neg_hi:[0,1]
	s_waitcnt lgkmcnt(8)
	v_pk_add_f32 v[50:51], v[50:51], v[138:139] op_sel_hi:[1,0] neg_lo:[0,1] neg_hi:[0,1]
	s_waitcnt lgkmcnt(7)
	v_pk_add_f32 v[52:53], v[52:53], v[138:139] op_sel_hi:[1,0] neg_lo:[0,1] neg_hi:[0,1]
	s_waitcnt lgkmcnt(6)
	v_pk_add_f32 v[54:55], v[54:55], v[138:139] op_sel_hi:[1,0] neg_lo:[0,1] neg_hi:[0,1]
	s_waitcnt lgkmcnt(5)
	v_pk_add_f32 v[56:57], v[56:57], v[138:139] op_sel_hi:[1,0] neg_lo:[0,1] neg_hi:[0,1]
	s_waitcnt lgkmcnt(4)
	v_pk_add_f32 v[58:59], v[58:59], v[138:139] op_sel_hi:[1,0] neg_lo:[0,1] neg_hi:[0,1]
	s_waitcnt lgkmcnt(3)
	v_pk_add_f32 v[60:61], v[60:61], v[138:139] op_sel_hi:[1,0] neg_lo:[0,1] neg_hi:[0,1]
	s_waitcnt lgkmcnt(2)
	v_pk_add_f32 v[62:63], v[62:63], v[138:139] op_sel_hi:[1,0] neg_lo:[0,1] neg_hi:[0,1]
	s_waitcnt lgkmcnt(1)
	v_pk_add_f32 v[64:65], v[64:65], v[138:139] op_sel_hi:[1,0] neg_lo:[0,1] neg_hi:[0,1]
	s_waitcnt lgkmcnt(0)
	v_pk_add_f32 v[66:67], v[66:67], v[138:139] op_sel_hi:[1,0] neg_lo:[0,1] neg_hi:[0,1]
	s_xor_b64 s[36:37], s[10:11], -1
	v_mfma_f32_32x32x16_bf16 v[36:51], v[120:123], v[72:75], v[36:51]
	v_mfma_f32_32x32x16_bf16 v[52:67], v[146:149], v[72:75], v[52:67]
	v_mfma_f32_32x32x16_bf16 v[36:51], v[124:127], v[76:79], v[36:51]
	ds_read_b64_tr_b16 v[124:125], v129 offset:34816
	ds_read_b64_tr_b16 v[126:127], v129 offset:37376
	ds_read_b64_tr_b16 v[122:123], v129 offset:37440
	ds_read_b64_tr_b16 v[120:121], v129 offset:34880
	v_mfma_f32_32x32x16_bf16 v[52:67], v[150:153], v[76:79], v[52:67]
	v_mfma_f32_32x32x16_bf16 v[36:51], v[154:157], v[80:83], v[36:51]
	v_mfma_f32_32x32x16_bf16 v[52:67], v[162:165], v[80:83], v[52:67]
	v_mfma_f32_32x32x16_bf16 v[36:51], v[158:161], v[84:87], v[36:51]
	v_mfma_f32_32x32x16_bf16 v[52:67], v[166:169], v[84:87], v[52:67]
	s_nop 11
	v_max_f32_e32 v68, v52, v52
	v_max_f32_e32 v70, v36, v36
	v_max_f32_e32 v68, v70, v68
	v_max3_f32 v68, v68, v37, v38
	v_max3_f32 v68, v68, v39, v40
	v_max3_f32 v68, v68, v41, v42
	v_max3_f32 v68, v68, v43, v44
	v_max3_f32 v68, v68, v45, v46
	v_max3_f32 v68, v68, v47, v48
	v_max3_f32 v68, v68, v49, v50
	v_max3_f32 v68, v68, v51, v53
	v_max3_f32 v68, v68, v54, v55
	v_max3_f32 v68, v68, v56, v57
	v_max3_f32 v68, v68, v58, v59
	v_max3_f32 v68, v68, v60, v61
	v_max3_f32 v68, v68, v62, v63
	v_max3_f32 v68, v68, v64, v65
	v_max3_f32 v68, v68, v66, v67
	v_mov_b32_e32 v70, v68
	s_nop 1
	v_permlane32_swap_b32_e32 v68, v70
	v_max_f32_e32 v70, v70, v70
	v_max_f32_e32 v68, v68, v68
	v_max_f32_e32 v70, v68, v70
	s_and_b64 vcc, exec, s[36:37]
	s_cbranch_vccz .LBB9_164
	v_cmp_lt_f32_e32 vcc, s59, v70
	s_mov_b64 s[38:39], 0
	s_mov_b64 s[36:37], 0
	s_cbranch_vccz .LBB9_133
	v_max_f32_e32 v68, v70, v70
	v_max_f32_e32 v68, 0, v68
	s_mov_b64 s[36:37], -1

.LBB9_148:
	s_add_i32 s70, s70, 1
	s_cmp_le_i32 s70, s43
	s_cselect_b64 s[38:39], -1, 0
	s_and_b64 s[38:39], s[2:3], s[38:39]
	s_cmp_ge_i32 s70, s44
	s_cselect_b64 s[70:71], -1, 0
	s_and_b64 s[38:39], s[38:39], s[70:71]
	s_andn2_b64 vcc, exec, s[38:39]
	s_cbranch_vccnz .LBB9_157
	v_add_u32_e32 v36, v35, v128
	v_add_u32_e32 v66, s65, v143
	ds_read_b128 v[120:123], v36 offset:17408
	ds_read_b128 v[124:127], v36 offset:17440
	ds_read_b128 v[146:149], v36 offset:26112
	ds_read_b128 v[150:153], v36 offset:26144
	ds_read_b128 v[154:157], v36 offset:17472
	ds_read_b128 v[158:161], v36 offset:17504
	ds_read_b128 v[162:165], v36 offset:26176
	ds_read_b128 v[166:169], v36 offset:26208
	v_add_u32_e32 v70, 0x12b10, v66
	ds_read2_b32 v[36:37], v70 offset0:59 offset1:58
	ds_read2_b32 v[38:39], v70 offset0:57 offset1:56
	ds_read2_b32 v[40:41], v70 offset0:51 offset1:50
	ds_read2_b32 v[42:43], v70 offset0:49 offset1:48
	ds_read2_b32 v[44:45], v70 offset0:43 offset1:42
	ds_read2_b32 v[46:47], v70 offset0:41 offset1:40
	ds_read2_b32 v[48:49], v70 offset0:35 offset1:34
	ds_read2_b32 v[50:51], v70 offset0:33 offset1:32
	ds_read2_b32 v[52:53], v70 offset0:27 offset1:26
	ds_read2_b32 v[54:55], v70 offset0:25 offset1:24
	ds_read2_b32 v[56:57], v70 offset0:19 offset1:18
	ds_read2_b32 v[58:59], v70 offset0:17 offset1:16
	ds_read2_b32 v[60:61], v70 offset0:11 offset1:10
	ds_read2_b32 v[62:63], v70 offset0:9 offset1:8
	ds_read2_b32 v[64:65], v70 offset0:3 offset1:2
	ds_read2_b32 v[66:67], v70 offset0:1 offset1:0
	s_waitcnt lgkmcnt(15)
	v_pk_add_f32 v[36:37], v[36:37], v[138:139] op_sel_hi:[1,0] neg_lo:[0,1] neg_hi:[0,1]
	s_waitcnt lgkmcnt(14)
	v_pk_add_f32 v[38:39], v[38:39], v[138:139] op_sel_hi:[1,0] neg_lo:[0,1] neg_hi:[0,1]
	s_waitcnt lgkmcnt(13)
	v_pk_add_f32 v[40:41], v[40:41], v[138:139] op_sel_hi:[1,0] neg_lo:[0,1] neg_hi:[0,1]
	s_waitcnt lgkmcnt(12)
	v_pk_add_f32 v[42:43], v[42:43], v[138:139] op_sel_hi:[1,0] neg_lo:[0,1] neg_hi:[0,1]
	s_waitcnt lgkmcnt(11)
	v_pk_add_f32 v[44:45], v[44:45], v[138:139] op_sel_hi:[1,0] neg_lo:[0,1] neg_hi:[0,1]
	s_waitcnt lgkmcnt(10)
	v_pk_add_f32 v[46:47], v[46:47], v[138:139] op_sel_hi:[1,0] neg_lo:[0,1] neg_hi:[0,1]
	s_waitcnt lgkmcnt(9)
	v_pk_add_f32 v[48:49], v[48:49], v[138:139] op_sel_hi:[1,0] neg_lo:[0,1] neg_hi:[0,1]
	s_waitcnt lgkmcnt(8)
	v_pk_add_f32 v[50:51], v[50:51], v[138:139] op_sel_hi:[1,0] neg_lo:[0,1] neg_hi:[0,1]
	s_waitcnt lgkmcnt(7)
	v_pk_add_f32 v[52:53], v[52:53], v[138:139] op_sel_hi:[1,0] neg_lo:[0,1] neg_hi:[0,1]
	s_waitcnt lgkmcnt(6)
	v_pk_add_f32 v[54:55], v[54:55], v[138:139] op_sel_hi:[1,0] neg_lo:[0,1] neg_hi:[0,1]
	s_waitcnt lgkmcnt(5)
	v_pk_add_f32 v[56:57], v[56:57], v[138:139] op_sel_hi:[1,0] neg_lo:[0,1] neg_hi:[0,1]
	s_waitcnt lgkmcnt(4)
	v_pk_add_f32 v[58:59], v[58:59], v[138:139] op_sel_hi:[1,0] neg_lo:[0,1] neg_hi:[0,1]
	s_waitcnt lgkmcnt(3)
	v_pk_add_f32 v[60:61], v[60:61], v[138:139] op_sel_hi:[1,0] neg_lo:[0,1] neg_hi:[0,1]
	s_waitcnt lgkmcnt(2)
	v_pk_add_f32 v[62:63], v[62:63], v[138:139] op_sel_hi:[1,0] neg_lo:[0,1] neg_hi:[0,1]
	s_waitcnt lgkmcnt(1)
	v_pk_add_f32 v[64:65], v[64:65], v[138:139] op_sel_hi:[1,0] neg_lo:[0,1] neg_hi:[0,1]
	s_waitcnt lgkmcnt(0)
	v_pk_add_f32 v[66:67], v[66:67], v[138:139] op_sel_hi:[1,0] neg_lo:[0,1] neg_hi:[0,1]
	v_mfma_f32_32x32x16_bf16 v[36:51], v[120:123], v[72:75], v[36:51]
	s_nop 0
	v_mfma_f32_32x32x16_bf16 v[52:67], v[146:149], v[72:75], v[52:67]
	v_mfma_f32_32x32x16_bf16 v[36:51], v[124:127], v[76:79], v[36:51]
	ds_read_b64_tr_b16 v[124:125], v129 offset:55296
	ds_read_b64_tr_b16 v[126:127], v129 offset:57856
	ds_read_b64_tr_b16 v[122:123], v129 offset:57920
	ds_read_b64_tr_b16 v[120:121], v129 offset:55360
	v_mfma_f32_32x32x16_bf16 v[52:67], v[150:153], v[76:79], v[52:67]
	v_mfma_f32_32x32x16_bf16 v[36:51], v[154:157], v[80:83], v[36:51]
	v_mfma_f32_32x32x16_bf16 v[52:67], v[162:165], v[80:83], v[52:67]
	v_mfma_f32_32x32x16_bf16 v[36:51], v[158:161], v[84:87], v[36:51]
	v_mfma_f32_32x32x16_bf16 v[52:67], v[166:169], v[84:87], v[52:67]
	s_nop 11
	v_max_f32_e32 v68, v52, v52
	v_max_f32_e32 v70, v36, v36
	v_max_f32_e32 v68, v70, v68
	v_max3_f32 v68, v68, v37, v38
	v_max3_f32 v68, v68, v39, v40
	v_max3_f32 v68, v68, v41, v42
	v_max3_f32 v68, v68, v43, v44
	v_max3_f32 v68, v68, v45, v46
	v_max3_f32 v68, v68, v47, v48
	v_max3_f32 v68, v68, v49, v50
	v_max3_f32 v68, v68, v51, v53
	v_max3_f32 v68, v68, v54, v55
	v_max3_f32 v68, v68, v56, v57
	v_max3_f32 v68, v68, v58, v59
	v_max3_f32 v68, v68, v60, v61
	v_max3_f32 v68, v68, v62, v63
	v_max3_f32 v68, v68, v64, v65
	v_max3_f32 v68, v68, v66, v67
	v_mov_b32_e32 v70, v68
	s_nop 1
	v_permlane32_swap_b32_e32 v68, v70
	v_max_f32_e32 v70, v70, v70
	v_max_f32_e32 v68, v68, v68
	v_max_f32_e32 v70, v68, v70
	s_and_b64 vcc, exec, s[36:37]
	s_cbranch_vccz .LBB9_165
	v_cmp_lt_f32_e32 vcc, s59, v70
	s_mov_b64 s[38:39], 0
	s_mov_b64 s[36:37], 0
	s_cbranch_vccz .LBB9_152
	v_max_f32_e32 v68, v70, v70
	v_max_f32_e32 v68, 0, v68
	s_mov_b64 s[36:37], -1
